# XCD-local grid seams (no L2 writeback, no cross-XCD hop) for all in-layer seams when a runtime census shows each blockIdx%8 class sits on one XCC; P0 and modulate seams stay full
# speedup vs baseline: 1.0412x; 1.0412x over previous
; #define LAS __attribute__((address_space(3)))
; #define TID0() (wave0 * 64 + hw_lane())
; __global__ void __launch_bounds__(512) fwd_kernel(Args a) {
;     extern __shared__ __attribute__((aligned(16))) unsigned char lds_raw[];
;     cg::grid_group grid = cg::this_grid();
;     LAS unsigned char* lds = (LAS unsigned char*)lds_raw;
;     const int wave0 = __builtin_amdgcn_readfirstlane(threadIdx.x >> 6), G = gridDim.x;
;     ...
;     const int lo = a.ph_lo, hi = a.ph_hi;
;     if (hi > 1000) grid.sync();
;     volatile LAS unsigned* bst = (volatile LAS unsigned*)(lds + 131072);
;     if (TID0() < 16) bst[TID0()] = 0u;
;     __syncthreads();
;     XcdBarrier bar = xcd_barrier_post((unsigned*)(a.ws + WS_BAR), bst);
_Z10fwd_kernel4Args:
	s_mov_b32 s100, 0
	v_writelane_b32 v255, s100, 41
	s_mov_b32 s101, 0
	s_load_dwordx8 s[76:83], s[0:1], 0x80
	s_load_dword s3, s[0:1], 0xa8
	s_load_dwordx2 s[88:89], s[0:1], 0xa0
	s_add_u32 s6, s0, 0xa0
	s_addc_u32 s7, s1, 0
	v_and_b32_e32 v1, 0x3ff, v0
	s_mov_b32 s66, s2
	s_movk_i32 s4, 0x3ff
	s_waitcnt lgkmcnt(0)
	s_cmpk_lt_i32 s83, 0x3e9
	v_readfirstlane_b32 s2, v1
	s_cbranch_scc1 .LBB0_12
	v_lshrrev_b32_e32 v2, 20, v0
	v_lshrrev_b32_e32 v0, 10, v0
	v_or_b32_e32 v0, v0, v2
	v_and_or_b32 v0, v0, s4, v1
	v_cmp_eq_u32_e32 vcc, 0, v0
	s_barrier
	s_and_saveexec_b64 s[4:5], vcc
	s_cbranch_execz .LBB0_11
	buffer_wbl2 sc1
	s_load_dwordx2 s[6:7], s[6:7], 0x58
	s_mov_b64 s[8:9], exec
	v_mbcnt_lo_u32_b32 v0, s8, 0
	v_mbcnt_hi_u32_b32 v0, s9, v0
	v_cmp_eq_u32_e32 vcc, 0, v0
	s_waitcnt lgkmcnt(0)
	s_load_dword s12, s[6:7], 0x28
	s_and_saveexec_b64 s[10:11], vcc
	s_cbranch_execz .LBB0_4
	s_bcnt1_i32_b64 s8, s[8:9]
	v_mov_b32_e32 v2, 0
	v_mov_b32_e32 v3, s8
	global_atomic_add v2, v2, v3, s[6:7] offset:32 sc0

; #define LAS __attribute__((address_space(3)))
; __device__ __forceinline__ unsigned xb_add(unsigned* p, unsigned v) { return __hip_atomic_fetch_add(p, v, __ATOMIC_RELAXED, __HIP_MEMORY_SCOPE_AGENT); }
; __device__ __forceinline__ unsigned xb_xcc_id() { return (unsigned)__builtin_amdgcn_s_getreg((3 << 11) | 20) & 0xFu; }
; __device__ __forceinline__ XcdBarrier xcd_barrier_post(unsigned* bar, volatile LAS unsigned* st) {
;     XcdBarrier b; b.bar = bar; b.x = xb_xcc_id(); b.st = st;
;     if (threadIdx.x == 0) (void)xb_add(&bar[XB_XCNT(b.x)], 1u);
;     return b;
; }
.LBB0_14:
	s_or_b64 exec, exec, s[4:5]
	s_add_u32 s4, s80, 0x1780000
	s_addc_u32 s5, s81, 0
	v_writelane_b32 v253, s4, 1
	s_waitcnt lgkmcnt(0)
	s_barrier
	v_writelane_b32 v253, s5, 2
	s_getreg_b32 s4, hwreg(HW_REG_XCC_ID, 0, 4)
	s_and_b32 s33, s4, 15
	v_cmp_eq_u32_e64 s[6:7], 0, v1
	s_mov_b64 s[4:5], exec
	s_nop 0
	v_writelane_b32 v253, s6, 3
	s_nop 1
	v_writelane_b32 v253, s7, 4
	s_and_b64 s[6:7], s[4:5], s[6:7]
	s_mov_b64 exec, s[6:7]
	s_cbranch_execz .LBB0_17
	s_mov_b64 s[6:7], exec
	v_mbcnt_lo_u32_b32 v0, s6, 0
	v_mbcnt_hi_u32_b32 v0, s7, v0
	v_cmp_eq_u32_e32 vcc, 0, v0
	s_and_b64 s[8:9], exec, vcc
	s_mov_b64 exec, s[8:9]
	s_cbranch_execz .LBB0_17
	s_bcnt1_i32_b64 s6, s[6:7]
	s_lshl_b32 s8, s33, 8
	v_mov_b32_e32 v1, s6
	v_readlane_b32 s6, v253, 1
	v_mov_b32_e32 v0, s8
	v_readlane_b32 s7, v253, 2
	s_nop 4
	global_atomic_add v0, v1, s[6:7] offset:1024
	s_and_b32 s8, s66, 7
	s_lshl_b32 s8, s8, 6
	s_add_i32 s8, s8, 0x3800
	s_lshl_b32 s9, 1, s33
	v_mov_b32_e32 v2, s8
	v_mov_b32_e32 v3, s9
	global_atomic_or v2, v3, s[6:7]

; #define LAUNDER() int tp = TID0(); const int tid = tp, lane = tp & 63, wave = __builtin_amdgcn_readfirstlane(tp >> 6); (void)tid; (void)lane; (void)wave
; #define SEAM(k) do { if (lo <= (k) && (k) + 1 < hi) { XcdBarrier b2_ = bar; asm volatile("" : "+s"(b2_.bar)); xcd_barrier(b2_); } } while (0)
; __global__ void __launch_bounds__(512) fwd_kernel(Args a) {
;     ...
;     if (IN(0) && EN_P0) { LAUNDER(); phase0(a.in[1], a.in[3], a.in[5], a.in[15], WIN, WOUT, MODP, KMAX, WDT, lds, tid, G); }
;     SEAM(0);
.LBB0_88:
	s_or_b64 exec, exec, s[34:35]
	s_waitcnt lgkmcnt(0)
	s_barrier
	v_mbcnt_lo_u32_b32 v0, -1, 0
	v_mbcnt_hi_u32_b32 v0, -1, v0
	v_and_b32_e32 v0, 7, v0
	v_lshlrev_b32_e32 v0, 6, v0
	s_add_u32 s0, s80, 0x1783800
	s_addc_u32 s1, s81, 0
	global_load_dword v1, v0, s[0:1] sc1
	s_waitcnt vmcnt(0)
	v_add_u32_e32 v2, -1, v1
	v_and_b32_e32 v2, v2, v1
	v_cmp_eq_u32_e32 vcc, 0, v2
	v_cmp_ne_u32_e64 s[0:1], 0, v1
	s_and_b64 vcc, vcc, s[0:1]
	s_cmp_eq_u64 vcc, exec
	s_cselect_b32 s0, 1, 0
	v_writelane_b32 v255, s0, 41

; __device__ __forceinline__ unsigned xb_ld(unsigned* p)              { return __hip_atomic_load(p, __ATOMIC_RELAXED, __HIP_MEMORY_SCOPE_AGENT); }
; __device__ __forceinline__ unsigned xb_add(unsigned* p, unsigned v) { return __hip_atomic_fetch_add(p, v, __ATOMIC_RELAXED, __HIP_MEMORY_SCOPE_AGENT); }
; #define XB_SPIN(cond, bar) do { unsigned _sp = 0; while (cond) { __builtin_amdgcn_s_sleep(1); \
;     if ((++_sp & 255u) == 0u) { if (xb_ld(&(bar)[XB_TMO])) break; if (_sp > XB_SPIN_CAP) { atomicAdd(&(bar)[XB_TMO], 1u); break; } } } } while (0)
; __device__ __forceinline__ void xcd_barrier(const XcdBarrier& b) {
;     ...
;         const unsigned old = xb_add(&bar[XB_XSUB(b.x)], 1u);
;         const unsigned gen = old / nloc;
;         if (old + 1u == (gen + 1u) * nloc) {
;             __builtin_amdgcn_fence(__ATOMIC_RELEASE, "agent");
;             asm volatile("s_waitcnt vmcnt(0)" ::: "memory");
;             const unsigned og = xb_add(&bar[XB_TOP], 1u);
;             const unsigned tg = og / nx;
;             if (og + 1u == (tg + 1u) * nx) xb_add(&bar[XB_TOPGEN], 1u);
;             else XB_SPIN(xb_ld(&bar[XB_TOPGEN]) == tg, bar);
.LBB0_231:
	s_andn2_saveexec_b64 s[30:31], s[30:31]
	s_cbranch_execz .LBB0_247
	v_readlane_b32 s36, v255, 41
	s_cmp_lg_u32 s36, 0
	s_cbranch_scc1 .Lseam_loc5
	v_mov_b32_e32 v5, s26
	v_add_co_u32_e32 v6, vcc, 0x3000, v5
	v_mov_b32_e32 v5, s27
	buffer_wbl2 sc1
	s_waitcnt vmcnt(0)
	v_addc_co_u32_e32 v7, vcc, 0, v5, vcc
	flat_atomic_add v5, v[6:7], v252 offset:1024 sc0
	v_cvt_f32_u32_e32 v6, v4
	v_sub_u32_e32 v7, 0, v4
	s_mov_b64 s[38:39], -1
	v_rcp_iflag_f32_e32 v6, v6
	s_nop 0
	v_mul_f32_e32 v6, 0x4f7ffffe, v6
	v_cvt_u32_f32_e32 v6, v6
	v_mul_lo_u32 v7, v7, v6
	v_mul_hi_u32 v7, v6, v7
	v_add_u32_e32 v6, v6, v7
	s_waitcnt vmcnt(0) lgkmcnt(0)
	v_mul_hi_u32 v6, v5, v6
	v_mul_lo_u32 v7, v6, v4
	v_sub_u32_e32 v7, v5, v7
	v_cmp_ge_u32_e32 vcc, v7, v4
	v_add_u32_e32 v8, 1, v6
	s_nop 0
	v_cndmask_b32_e32 v6, v6, v8, vcc
	v_sub_u32_e32 v8, v7, v4
	v_cndmask_b32_e32 v7, v7, v8, vcc
	v_cmp_ge_u32_e32 vcc, v7, v4
	v_add_u32_e32 v7, 1, v6
	s_nop 0
	v_cndmask_b32_e32 v6, v6, v7, vcc
	v_add_u32_e32 v7, 1, v5
	v_mad_u64_u32 v[4:5], s[30:31], v4, v6, v[4:5]
	s_add_u32 s30, s26, 0x3500
	s_addc_u32 s31, s27, 0
	v_cmp_ne_u32_e32 vcc, v7, v4
	v_mov_b64_e32 v[4:5], s[30:31]
	s_and_saveexec_b64 s[36:37], vcc
	s_cbranch_execz .LBB0_244
	v_mov_b64_e32 v[4:5], s[30:31]
	flat_load_dword v4, v[4:5] sc1
	s_mov_b64 s[42:43], 0
	s_waitcnt vmcnt(0) lgkmcnt(0)
	v_cmp_eq_u32_e32 vcc, v4, v6
	s_and_saveexec_b64 s[40:41], vcc
	s_cbranch_execz .LBB0_243
	s_add_u32 s38, s26, 0x200
	s_addc_u32 s39, s27, 0
	s_mov_b32 s16, 1
	s_mov_b64 s[26:27], 0
	s_branch .LBB0_236

; __device__ __forceinline__ unsigned xb_add(unsigned* p, unsigned v) { return __hip_atomic_fetch_add(p, v, __ATOMIC_RELAXED, __HIP_MEMORY_SCOPE_AGENT); }
; __device__ __forceinline__ void xcd_barrier(const XcdBarrier& b) {
;     ...
;             __builtin_amdgcn_fence(__ATOMIC_ACQUIRE, "agent");
;             xb_add(&bar[XB_XGEN(b.x)], 1u);
;             asm volatile("s_waitcnt vmcnt(0)" ::: "memory");
.Lseam_loc5:
	v_mov_b32_e32 v4, s5
	v_add_co_u32_e32 v4, vcc, 0x2000, v4
	v_mov_b32_e32 v5, s4
	s_nop 0
	v_addc_co_u32_e32 v5, vcc, 0, v5, vcc
	s_waitcnt vmcnt(0) lgkmcnt(0)
	buffer_inv sc1
	flat_atomic_add v[4:5], v252 offset:1024
	s_waitcnt vmcnt(0)

; __device__ __forceinline__ unsigned xb_ld(unsigned* p)              { return __hip_atomic_load(p, __ATOMIC_RELAXED, __HIP_MEMORY_SCOPE_AGENT); }
; __device__ __forceinline__ unsigned xb_add(unsigned* p, unsigned v) { return __hip_atomic_fetch_add(p, v, __ATOMIC_RELAXED, __HIP_MEMORY_SCOPE_AGENT); }
; #define XB_SPIN(cond, bar) do { unsigned _sp = 0; while (cond) { __builtin_amdgcn_s_sleep(1); \
;     if ((++_sp & 255u) == 0u) { if (xb_ld(&(bar)[XB_TMO])) break; if (_sp > XB_SPIN_CAP) { atomicAdd(&(bar)[XB_TMO], 1u); break; } } } } while (0)
; __device__ __forceinline__ void xcd_barrier(const XcdBarrier& b) {
;     ...
;         const unsigned old = xb_add(&bar[XB_XSUB(b.x)], 1u);
;         const unsigned gen = old / nloc;
;         if (old + 1u == (gen + 1u) * nloc) {
;             __builtin_amdgcn_fence(__ATOMIC_RELEASE, "agent");
;             asm volatile("s_waitcnt vmcnt(0)" ::: "memory");
;             const unsigned og = xb_add(&bar[XB_TOP], 1u);
;             const unsigned tg = og / nx;
;             if (og + 1u == (tg + 1u) * nx) xb_add(&bar[XB_TOPGEN], 1u);
;             else XB_SPIN(xb_ld(&bar[XB_TOPGEN]) == tg, bar);
.LBB0_553:
	s_andn2_saveexec_b64 s[30:31], s[30:31]
	s_cbranch_execz .LBB0_569
	v_readlane_b32 s36, v255, 41
	s_cmp_lg_u32 s36, 0
	s_cbranch_scc1 .Lseam_loc2
	v_mov_b32_e32 v5, s20
	v_add_co_u32_e32 v6, vcc, 0x3000, v5
	v_mov_b32_e32 v5, s21
	buffer_wbl2 sc1
	s_waitcnt vmcnt(0)
	v_addc_co_u32_e32 v7, vcc, 0, v5, vcc
	flat_atomic_add v5, v[6:7], v252 offset:1024 sc0
	v_cvt_f32_u32_e32 v6, v4
	v_sub_u32_e32 v7, 0, v4
	s_mov_b64 s[38:39], -1
	v_rcp_iflag_f32_e32 v6, v6
	s_nop 0
	v_mul_f32_e32 v6, 0x4f7ffffe, v6
	v_cvt_u32_f32_e32 v6, v6
	v_mul_lo_u32 v7, v7, v6
	v_mul_hi_u32 v7, v6, v7
	v_add_u32_e32 v6, v6, v7
	s_waitcnt vmcnt(0) lgkmcnt(0)
	v_mul_hi_u32 v6, v5, v6
	v_mul_lo_u32 v7, v6, v4
	v_sub_u32_e32 v7, v5, v7
	v_cmp_ge_u32_e32 vcc, v7, v4
	v_add_u32_e32 v8, 1, v6
	s_nop 0
	v_cndmask_b32_e32 v6, v6, v8, vcc
	v_sub_u32_e32 v8, v7, v4
	v_cndmask_b32_e32 v7, v7, v8, vcc
	v_cmp_ge_u32_e32 vcc, v7, v4
	v_add_u32_e32 v7, 1, v6
	s_nop 0
	v_cndmask_b32_e32 v6, v6, v7, vcc
	v_add_u32_e32 v7, 1, v5
	v_mad_u64_u32 v[4:5], s[30:31], v4, v6, v[4:5]
	s_add_u32 s30, s20, 0x3500
	s_addc_u32 s31, s21, 0
	v_cmp_ne_u32_e32 vcc, v7, v4
	v_mov_b64_e32 v[4:5], s[30:31]
	s_and_saveexec_b64 s[36:37], vcc
	s_cbranch_execz .LBB0_566
	v_mov_b64_e32 v[4:5], s[30:31]
	flat_load_dword v4, v[4:5] sc1
	s_mov_b64 s[42:43], 0
	s_waitcnt vmcnt(0) lgkmcnt(0)
	v_cmp_eq_u32_e32 vcc, v4, v6
	s_and_saveexec_b64 s[40:41], vcc
	s_cbranch_execz .LBB0_565
	s_add_u32 s38, s20, 0x200
	s_addc_u32 s39, s21, 0
	s_mov_b32 s16, 1
	s_mov_b64 s[20:21], 0
	s_branch .LBB0_558

; __device__ __forceinline__ void xcd_barrier(const XcdBarrier& b) {
;     ...
;     }
;     __syncthreads();
; }
.Lseam_loc1_far:
	s_getpc_b64 s[98:99]

; __device__ __forceinline__ unsigned xb_ld(unsigned* p)              { return __hip_atomic_load(p, __ATOMIC_RELAXED, __HIP_MEMORY_SCOPE_AGENT); }
; __device__ __forceinline__ unsigned xb_add(unsigned* p, unsigned v) { return __hip_atomic_fetch_add(p, v, __ATOMIC_RELAXED, __HIP_MEMORY_SCOPE_AGENT); }
; #define XB_SPIN(cond, bar) do { unsigned _sp = 0; while (cond) { __builtin_amdgcn_s_sleep(1); \
;     if ((++_sp & 255u) == 0u) { if (xb_ld(&(bar)[XB_TMO])) break; if (_sp > XB_SPIN_CAP) { atomicAdd(&(bar)[XB_TMO], 1u); break; } } } } while (0)
; __device__ __forceinline__ void xcd_barrier(const XcdBarrier& b) {
;     ...
;         const unsigned old = xb_add(&bar[XB_XSUB(b.x)], 1u);
;         const unsigned gen = old / nloc;
;         if (old + 1u == (gen + 1u) * nloc) {
;             __builtin_amdgcn_fence(__ATOMIC_RELEASE, "agent");
;             asm volatile("s_waitcnt vmcnt(0)" ::: "memory");
;             const unsigned og = xb_add(&bar[XB_TOP], 1u);
;             const unsigned tg = og / nx;
;             if (og + 1u == (tg + 1u) * nx) xb_add(&bar[XB_TOPGEN], 1u);
;             else XB_SPIN(xb_ld(&bar[XB_TOPGEN]) == tg, bar);
;             __builtin_amdgcn_fence(__ATOMIC_ACQUIRE, "agent");
;             xb_add(&bar[XB_XGEN(b.x)], 1u);
;             asm volatile("s_waitcnt vmcnt(0)" ::: "memory");
.LBB0_731:
	v_readlane_b32 s26, v255, 41
	s_cmp_lg_u32 s26, 0
	s_cbranch_scc0 .Lseam_loc1_full
	v_mov_b32_e32 v4, s4
	v_add_co_u32_e32 v4, vcc, 0x2000, v4
	v_mov_b32_e32 v5, s2
	s_nop 0
	v_addc_co_u32_e32 v5, vcc, 0, v5, vcc
	s_waitcnt vmcnt(0) lgkmcnt(0)
	buffer_inv sc1
	flat_atomic_add v[4:5], v252 offset:1024
	s_waitcnt vmcnt(0)
	s_branch .Lseam_loc1_far
